# opt27: every workgroup's leader thread issues buffer_wbl2 on arrival at the grid barrier (the XCD's dirty lines are written back progressively instead of all behind the last local arriver); on v068
# baseline (speedup 1.0000x reference)
.LBB0_133:
	s_cmp_eq_u32 s75, 2
	s_cbranch_scc1 .LBB0_187
	s_waitcnt vmcnt(0)
	s_barrier
	s_and_saveexec_b64 s[0:1], s[92:93]
	s_cbranch_execz .LBB0_186
	buffer_wbl2 sc1
	s_add_i32 s3, 0, 0x27fc0
	v_mov_b32_e32 v0, s3
	s_waitcnt vmcnt(0) expcnt(0) lgkmcnt(0)
	ds_read_b32 v2, v0
	s_add_i32 s3, 0, 0x27fc4
	v_mov_b32_e32 v0, s3
	ds_read_b32 v0, v0
	s_waitcnt lgkmcnt(1)
	v_cmp_ne_u32_e32 vcc, 0, v2
	s_cbranch_vccnz .LBB0_150
	s_add_u32 s4, s70, 0x4200
	s_addc_u32 s5, s71, 0
	s_add_u32 s6, s70, 0x4400
	s_addc_u32 s7, s71, 0
	s_add_u32 s8, s70, 0x4500
	s_addc_u32 s9, s71, 0
	s_add_u32 s10, s70, 0x4600
	s_addc_u32 s11, s71, 0
	s_add_u32 s14, s70, 0x4700
	s_addc_u32 s15, s71, 0
	s_add_u32 s16, s70, 0x4800
	s_addc_u32 s17, s71, 0
	s_add_u32 s18, s70, 0x4900
	s_addc_u32 s19, s71, 0
	s_add_u32 s20, s70, 0x4a00
	s_addc_u32 s21, s71, 0
	s_add_u32 s22, s70, 0x4b00
	s_addc_u32 s23, s71, 0
	s_add_u32 s26, s70, 0x4c00
	s_addc_u32 s27, s71, 0
	s_add_u32 s28, s70, 0x4d00
	s_addc_u32 s29, s71, 0
	s_add_u32 s40, s70, 0x4e00
	s_addc_u32 s41, s71, 0
	s_add_u32 s42, s70, 0x4f00
	s_addc_u32 s43, s71, 0
	s_add_u32 s48, s70, 0x5000
	s_addc_u32 s49, s71, 0
	s_add_u32 s50, s70, 0x5100
	s_addc_u32 s51, s71, 0
	s_add_u32 s52, s70, 0x5200
	s_addc_u32 s53, s71, 0
	s_mul_i32 s3, s73, s96
	s_add_u32 s54, s70, 0x5300
	s_mul_i32 s3, s3, s72
	s_addc_u32 s55, s71, 0
	s_mov_b32 s12, 1
	v_mov_b32_e32 v16, 0
	s_branch .LBB0_138

.LBB0_187:
	s_sub_i32 s0, s75, s74
	s_cmp_lt_i32 s0, 3
	s_cbranch_scc1 .LBB0_194
	s_and_saveexec_b64 s[0:1], s[92:93]
	s_cbranch_execz .LBB0_192
	buffer_wbl2 sc1
	s_add_u32 s3, s70, 0xa000
	s_addc_u32 s6, s71, 0
	s_ashr_i32 s4, s72, 31
	s_lshr_b32 s4, s4, 29
	s_add_i32 s4, s72, s4
	v_cndmask_b32_e64 v0, 0, 1, s[34:35]
	s_ashr_i32 s7, s4, 3
	s_mov_b64 s[4:5], 0
	v_mov_b32_e32 v1, 0

.LBB0_250:
	s_waitcnt vmcnt(0)
	s_waitcnt vmcnt(0) lgkmcnt(0)
	s_barrier
	s_and_saveexec_b64 s[0:1], s[92:93]
	s_cbranch_execz .LBB0_302
	buffer_wbl2 sc1
	s_add_i32 s3, 0, 0x27fc0
	v_mov_b32_e32 v0, s3
	s_waitcnt vmcnt(0) expcnt(0) lgkmcnt(0)
	ds_read_b32 v2, v0
	s_add_i32 s3, 0, 0x27fc4
	v_mov_b32_e32 v0, s3
	ds_read_b32 v0, v0
	s_waitcnt lgkmcnt(1)
	v_cmp_ne_u32_e32 vcc, 0, v2
	s_cbranch_vccnz .LBB0_266
	s_add_u32 s4, s70, 0x4200
	s_addc_u32 s5, s71, 0
	s_add_u32 s6, s70, 0x4400
	s_addc_u32 s7, s71, 0
	s_add_u32 s8, s70, 0x4500
	s_addc_u32 s9, s71, 0
	s_add_u32 s10, s70, 0x4600
	s_addc_u32 s11, s71, 0
	s_add_u32 s20, s70, 0x4700
	s_addc_u32 s21, s71, 0
	s_add_u32 s22, s70, 0x4800
	s_addc_u32 s23, s71, 0
	s_add_u32 s26, s70, 0x4900
	s_addc_u32 s27, s71, 0
	s_add_u32 s28, s70, 0x4a00
	s_addc_u32 s29, s71, 0
	s_add_u32 s40, s70, 0x4b00
	s_addc_u32 s41, s71, 0
	s_add_u32 s42, s70, 0x4c00
	s_addc_u32 s43, s71, 0
	s_add_u32 s48, s70, 0x4d00
	s_addc_u32 s49, s71, 0
	s_add_u32 s50, s70, 0x4e00
	s_addc_u32 s51, s71, 0
	s_add_u32 s52, s70, 0x4f00
	s_addc_u32 s53, s71, 0
	s_add_u32 s54, s70, 0x5000
	s_addc_u32 s55, s71, 0
	s_add_u32 s56, s70, 0x5100
	s_addc_u32 s57, s71, 0
	s_add_u32 s58, s70, 0x5200
	s_addc_u32 s59, s71, 0
	s_mul_i32 s3, s73, s96
	s_add_u32 s62, s70, 0x5300
	s_mul_i32 s3, s3, s72
	s_addc_u32 s63, s71, 0
	s_mov_b32 s12, 1
	v_mov_b32_e32 v16, 0
	s_branch .LBB0_254

.LBB0_311:
	s_or_b64 exec, exec, s[0:1]
	s_cmp_eq_u32 s75, 4
	s_cbranch_scc1 .LBB0_365
	s_waitcnt vmcnt(0)
	s_waitcnt vmcnt(0) lgkmcnt(0)
	s_barrier
	s_and_saveexec_b64 s[0:1], s[92:93]
	s_cbranch_execz .LBB0_364
	buffer_wbl2 sc1
	s_add_i32 s3, 0, 0x27fc0
	v_mov_b32_e32 v0, s3
	s_waitcnt vmcnt(0) expcnt(0) lgkmcnt(0)
	ds_read_b32 v2, v0
	s_add_i32 s3, 0, 0x27fc4
	v_mov_b32_e32 v0, s3
	ds_read_b32 v0, v0
	s_waitcnt lgkmcnt(1)
	v_cmp_ne_u32_e32 vcc, 0, v2
	s_cbranch_vccnz .LBB0_328
	s_add_u32 s4, s70, 0x4200
	s_addc_u32 s5, s71, 0
	s_add_u32 s6, s70, 0x4400
	s_addc_u32 s7, s71, 0
	s_add_u32 s8, s70, 0x4500
	s_addc_u32 s9, s71, 0
	s_add_u32 s10, s70, 0x4600
	s_addc_u32 s11, s71, 0
	s_add_u32 s22, s70, 0x4700
	s_addc_u32 s23, s71, 0
	s_add_u32 s26, s70, 0x4800
	s_addc_u32 s27, s71, 0
	s_add_u32 s28, s70, 0x4900
	s_addc_u32 s29, s71, 0
	s_add_u32 s40, s70, 0x4a00
	s_addc_u32 s41, s71, 0
	s_add_u32 s42, s70, 0x4b00
	s_addc_u32 s43, s71, 0
	s_add_u32 s48, s70, 0x4c00
	s_addc_u32 s49, s71, 0
	s_add_u32 s50, s70, 0x4d00
	s_addc_u32 s51, s71, 0
	s_add_u32 s52, s70, 0x4e00
	s_addc_u32 s53, s71, 0
	s_add_u32 s54, s70, 0x4f00
	s_addc_u32 s55, s71, 0
	s_add_u32 s56, s70, 0x5000
	s_addc_u32 s57, s71, 0
	s_add_u32 s58, s70, 0x5100
	s_addc_u32 s59, s71, 0
	s_add_u32 s62, s70, 0x5200
	s_addc_u32 s63, s71, 0
	s_mul_i32 s3, s73, s96
	s_add_u32 s64, s70, 0x5300
	s_mul_i32 s3, s3, s72
	s_addc_u32 s65, s71, 0
	s_mov_b32 s12, 1
	v_mov_b32_e32 v16, 0
	s_branch .LBB0_316

.LBB0_409:
	s_waitcnt vmcnt(0)
	s_waitcnt vmcnt(0) lgkmcnt(0)
	s_barrier
	s_and_saveexec_b64 s[0:1], s[92:93]
	s_cbranch_execz .LBB0_461
	buffer_wbl2 sc1
	s_add_i32 s3, 0, 0x27fc0
	v_mov_b32_e32 v0, s3
	s_waitcnt vmcnt(0) expcnt(0) lgkmcnt(0)
	ds_read_b32 v2, v0
	s_add_i32 s3, 0, 0x27fc4
	v_mov_b32_e32 v0, s3
	ds_read_b32 v0, v0
	s_waitcnt lgkmcnt(1)
	v_cmp_ne_u32_e32 vcc, 0, v2
	s_cbranch_vccnz .LBB0_425
	s_add_u32 s4, s70, 0x4200
	s_addc_u32 s5, s71, 0
	s_add_u32 s6, s70, 0x4400
	s_addc_u32 s7, s71, 0
	s_add_u32 s8, s70, 0x4500
	s_addc_u32 s9, s71, 0
	s_add_u32 s10, s70, 0x4600
	s_addc_u32 s11, s71, 0
	s_add_u32 s22, s70, 0x4700
	s_addc_u32 s23, s71, 0
	s_add_u32 s26, s70, 0x4800
	s_addc_u32 s27, s71, 0
	s_add_u32 s28, s70, 0x4900
	s_addc_u32 s29, s71, 0
	s_add_u32 s40, s70, 0x4a00
	s_addc_u32 s41, s71, 0
	s_add_u32 s42, s70, 0x4b00
	s_addc_u32 s43, s71, 0
	s_add_u32 s48, s70, 0x4c00
	s_addc_u32 s49, s71, 0
	s_add_u32 s50, s70, 0x4d00
	s_addc_u32 s51, s71, 0
	s_add_u32 s52, s70, 0x4e00
	s_addc_u32 s53, s71, 0
	s_add_u32 s54, s70, 0x4f00
	s_addc_u32 s55, s71, 0
	s_add_u32 s56, s70, 0x5000
	s_addc_u32 s57, s71, 0
	s_add_u32 s58, s70, 0x5100
	s_addc_u32 s59, s71, 0
	s_add_u32 s62, s70, 0x5200
	s_addc_u32 s63, s71, 0
	s_mul_i32 s3, s73, s96
	s_add_u32 s64, s70, 0x5300
	s_mul_i32 s3, s3, s72
	s_addc_u32 s65, s71, 0
	s_mov_b32 s12, 1
	v_mov_b32_e32 v16, 0
	s_branch .LBB0_413

.LBB0_483:
	s_cmp_eq_u32 s75, 6
	s_cbranch_scc1 .LBB0_537
	s_waitcnt vmcnt(0)
	s_waitcnt vmcnt(0)
	s_barrier
	s_and_saveexec_b64 s[0:1], s[92:93]
	s_cbranch_execz .LBB0_536
	buffer_wbl2 sc1
	s_add_i32 s3, 0, 0x27fc0
	v_mov_b32_e32 v0, s3
	s_waitcnt vmcnt(0) expcnt(0) lgkmcnt(0)
	ds_read_b32 v2, v0
	s_add_i32 s3, 0, 0x27fc4
	v_mov_b32_e32 v0, s3
	ds_read_b32 v0, v0
	s_waitcnt lgkmcnt(1)
	v_cmp_ne_u32_e32 vcc, 0, v2
	s_cbranch_vccnz .LBB0_500
	s_add_u32 s4, s70, 0x4200
	s_addc_u32 s5, s71, 0
	s_add_u32 s6, s70, 0x4400
	s_addc_u32 s7, s71, 0
	s_add_u32 s8, s70, 0x4500
	s_addc_u32 s9, s71, 0
	s_add_u32 s10, s70, 0x4600
	s_addc_u32 s11, s71, 0
	s_add_u32 s22, s70, 0x4700
	s_addc_u32 s23, s71, 0
	s_add_u32 s26, s70, 0x4800
	s_addc_u32 s27, s71, 0
	s_add_u32 s28, s70, 0x4900
	s_addc_u32 s29, s71, 0
	s_add_u32 s40, s70, 0x4a00
	s_addc_u32 s41, s71, 0
	s_add_u32 s42, s70, 0x4b00
	s_addc_u32 s43, s71, 0
	s_add_u32 s48, s70, 0x4c00
	s_addc_u32 s49, s71, 0
	s_add_u32 s50, s70, 0x4d00
	s_addc_u32 s51, s71, 0
	s_add_u32 s52, s70, 0x4e00
	s_addc_u32 s53, s71, 0
	s_add_u32 s54, s70, 0x4f00
	s_addc_u32 s55, s71, 0
	s_add_u32 s56, s70, 0x5000
	s_addc_u32 s57, s71, 0
	s_add_u32 s58, s70, 0x5100
	s_addc_u32 s59, s71, 0
	s_add_u32 s62, s70, 0x5200
	s_addc_u32 s63, s71, 0
	s_mul_i32 s3, s73, s96
	s_add_u32 s64, s70, 0x5300
	s_mul_i32 s3, s3, s72
	s_addc_u32 s65, s71, 0
	s_mov_b32 s12, 1
	v_mov_b32_e32 v16, 0
	s_branch .LBB0_488

.LBB0_894:
	s_cmp_eq_u32 s75, 9
	s_cbranch_scc1 .LBB0_948
	s_waitcnt vmcnt(0)
	s_waitcnt vmcnt(0) lgkmcnt(0)
	s_barrier
	s_and_saveexec_b64 s[0:1], s[92:93]
	s_cbranch_execz .LBB0_947
	buffer_wbl2 sc1
	s_add_i32 s3, 0, 0x27fc0
	v_mov_b32_e32 v0, s3
	s_waitcnt vmcnt(0) expcnt(0) lgkmcnt(0)
	ds_read_b32 v2, v0
	s_add_i32 s3, 0, 0x27fc4
	v_mov_b32_e32 v0, s3
	ds_read_b32 v0, v0
	s_waitcnt lgkmcnt(1)
	v_cmp_ne_u32_e32 vcc, 0, v2
	s_cbranch_vccnz .LBB0_911
	s_add_u32 s4, s70, 0x4200
	s_addc_u32 s5, s71, 0
	s_add_u32 s6, s70, 0x4400
	s_addc_u32 s7, s71, 0
	s_add_u32 s8, s70, 0x4500
	s_addc_u32 s9, s71, 0
	s_add_u32 s10, s70, 0x4600
	s_addc_u32 s11, s71, 0
	s_add_u32 s22, s70, 0x4700
	s_addc_u32 s23, s71, 0
	s_add_u32 s26, s70, 0x4800
	s_addc_u32 s27, s71, 0
	s_add_u32 s28, s70, 0x4900
	s_addc_u32 s29, s71, 0
	s_add_u32 s30, s70, 0x4a00
	s_addc_u32 s31, s71, 0
	s_add_u32 s36, s70, 0x4b00
	s_addc_u32 s37, s71, 0
	s_add_u32 s38, s70, 0x4c00
	s_addc_u32 s39, s71, 0
	s_add_u32 s40, s70, 0x4d00
	s_addc_u32 s41, s71, 0
	s_add_u32 s42, s70, 0x4e00
	s_addc_u32 s43, s71, 0
	s_add_u32 s48, s70, 0x4f00
	s_addc_u32 s49, s71, 0
	s_add_u32 s50, s70, 0x5000
	s_addc_u32 s51, s71, 0
	s_add_u32 s52, s70, 0x5100
	s_addc_u32 s53, s71, 0
	s_add_u32 s54, s70, 0x5200
	s_addc_u32 s55, s71, 0
	s_mul_i32 s3, s73, s96
	s_add_u32 s56, s70, 0x5300
	s_mul_i32 s3, s3, s72
	s_addc_u32 s57, s71, 0
	s_mov_b32 s12, 1
	v_mov_b32_e32 v16, 0
	s_branch .LBB0_899

.LBB0_992:
	s_waitcnt vmcnt(0)
	s_waitcnt vmcnt(0) lgkmcnt(0)
	s_barrier
	s_and_saveexec_b64 s[0:1], s[92:93]
	s_cbranch_execz .LBB0_1044
	buffer_wbl2 sc1
	s_add_i32 s3, 0, 0x27fc0
	v_mov_b32_e32 v0, s3
	s_waitcnt vmcnt(0) expcnt(0) lgkmcnt(0)
	ds_read_b32 v2, v0
	s_add_i32 s3, 0, 0x27fc4
	v_mov_b32_e32 v0, s3
	ds_read_b32 v0, v0
	s_waitcnt lgkmcnt(1)
	v_cmp_ne_u32_e32 vcc, 0, v2
	s_cbranch_vccnz .LBB0_1008
	s_add_u32 s4, s70, 0x4200
	s_addc_u32 s5, s71, 0
	s_add_u32 s6, s70, 0x4400
	s_addc_u32 s7, s71, 0
	s_add_u32 s8, s70, 0x4500
	s_addc_u32 s9, s71, 0
	s_add_u32 s10, s70, 0x4600
	s_addc_u32 s11, s71, 0
	s_add_u32 s22, s70, 0x4700
	s_addc_u32 s23, s71, 0
	s_add_u32 s26, s70, 0x4800
	s_addc_u32 s27, s71, 0
	s_add_u32 s28, s70, 0x4900
	s_addc_u32 s29, s71, 0
	s_add_u32 s30, s70, 0x4a00
	s_addc_u32 s31, s71, 0
	s_add_u32 s36, s70, 0x4b00
	s_addc_u32 s37, s71, 0
	s_add_u32 s38, s70, 0x4c00
	s_addc_u32 s39, s71, 0
	s_add_u32 s40, s70, 0x4d00
	s_addc_u32 s41, s71, 0
	s_add_u32 s42, s70, 0x4e00
	s_addc_u32 s43, s71, 0
	s_add_u32 s48, s70, 0x4f00
	s_addc_u32 s49, s71, 0
	s_add_u32 s50, s70, 0x5000
	s_addc_u32 s51, s71, 0
	s_add_u32 s52, s70, 0x5100
	s_addc_u32 s53, s71, 0
	s_add_u32 s54, s70, 0x5200
	s_addc_u32 s55, s71, 0
	s_mul_i32 s3, s73, s96
	s_add_u32 s56, s70, 0x5300
	s_mul_i32 s3, s3, s72
	s_addc_u32 s57, s71, 0
	s_mov_b32 s12, 1
	v_mov_b32_e32 v16, 0
	s_branch .LBB0_996

.LBB0_1066:
	s_cmp_eq_u32 s75, 11
	s_cbranch_scc1 .LBB0_1120
	s_waitcnt vmcnt(0)
	s_waitcnt vmcnt(0)
	s_barrier
	s_and_saveexec_b64 s[0:1], s[92:93]
	s_cbranch_execz .LBB0_1119
	buffer_wbl2 sc1
	s_add_i32 s3, 0, 0x27fc0
	v_mov_b32_e32 v0, s3
	s_waitcnt vmcnt(0) expcnt(0) lgkmcnt(0)
	ds_read_b32 v2, v0
	s_add_i32 s3, 0, 0x27fc4
	v_mov_b32_e32 v0, s3
	ds_read_b32 v0, v0
	s_waitcnt lgkmcnt(1)
	v_cmp_ne_u32_e32 vcc, 0, v2
	s_cbranch_vccnz .LBB0_1083
	s_add_u32 s4, s70, 0x4200
	s_addc_u32 s5, s71, 0
	s_add_u32 s6, s70, 0x4400
	s_addc_u32 s7, s71, 0
	s_add_u32 s8, s70, 0x4500
	s_addc_u32 s9, s71, 0
	s_add_u32 s10, s70, 0x4600
	s_addc_u32 s11, s71, 0
	s_add_u32 s22, s70, 0x4700
	s_addc_u32 s23, s71, 0
	s_add_u32 s26, s70, 0x4800
	s_addc_u32 s27, s71, 0
	s_add_u32 s28, s70, 0x4900
	s_addc_u32 s29, s71, 0
	s_add_u32 s30, s70, 0x4a00
	s_addc_u32 s31, s71, 0
	s_add_u32 s36, s70, 0x4b00
	s_addc_u32 s37, s71, 0
	s_add_u32 s38, s70, 0x4c00
	s_addc_u32 s39, s71, 0
	s_add_u32 s40, s70, 0x4d00
	s_addc_u32 s41, s71, 0
	s_add_u32 s42, s70, 0x4e00
	s_addc_u32 s43, s71, 0
	s_add_u32 s48, s70, 0x4f00
	s_addc_u32 s49, s71, 0
	s_add_u32 s50, s70, 0x5000
	s_addc_u32 s51, s71, 0
	s_add_u32 s52, s70, 0x5100
	s_addc_u32 s53, s71, 0
	s_add_u32 s54, s70, 0x5200
	s_addc_u32 s55, s71, 0
	s_mul_i32 s3, s73, s96
	s_add_u32 s56, s70, 0x5300
	s_mul_i32 s3, s3, s72
	s_addc_u32 s57, s71, 0
	s_mov_b32 s12, 1
	v_mov_b32_e32 v16, 0
	s_branch .LBB0_1071

.LBB0_1242:
	s_cmp_eq_u32 s75, 13
	s_cbranch_scc1 .LBB0_1296
	s_waitcnt vmcnt(0)
	s_waitcnt vmcnt(0)
	s_barrier
	s_and_saveexec_b64 s[0:1], s[92:93]
	s_cbranch_execz .LBB0_1295
	buffer_wbl2 sc1
	s_add_i32 s3, 0, 0x27fc0
	v_mov_b32_e32 v0, s3
	s_waitcnt vmcnt(0) expcnt(0) lgkmcnt(0)
	ds_read_b32 v2, v0
	s_add_i32 s3, 0, 0x27fc4
	v_mov_b32_e32 v0, s3
	ds_read_b32 v0, v0
	s_waitcnt lgkmcnt(1)
	v_cmp_ne_u32_e32 vcc, 0, v2
	s_cbranch_vccnz .LBB0_1259
	s_add_u32 s4, s70, 0x4200
	s_addc_u32 s5, s71, 0
	s_add_u32 s6, s70, 0x4400
	s_addc_u32 s7, s71, 0
	s_add_u32 s8, s70, 0x4500
	s_addc_u32 s9, s71, 0
	s_add_u32 s10, s70, 0x4600
	s_addc_u32 s11, s71, 0
	s_add_u32 s22, s70, 0x4700
	s_addc_u32 s23, s71, 0
	s_add_u32 s26, s70, 0x4800
	s_addc_u32 s27, s71, 0
	s_add_u32 s28, s70, 0x4900
	s_addc_u32 s29, s71, 0
	s_add_u32 s30, s70, 0x4a00
	s_addc_u32 s31, s71, 0
	s_add_u32 s36, s70, 0x4b00
	s_addc_u32 s37, s71, 0
	s_add_u32 s38, s70, 0x4c00
	s_addc_u32 s39, s71, 0
	s_add_u32 s40, s70, 0x4d00
	s_addc_u32 s41, s71, 0
	s_add_u32 s42, s70, 0x4e00
	s_addc_u32 s43, s71, 0
	s_add_u32 s48, s70, 0x4f00
	s_addc_u32 s49, s71, 0
	s_add_u32 s50, s70, 0x5000
	s_addc_u32 s51, s71, 0
	s_add_u32 s52, s70, 0x5100
	s_addc_u32 s53, s71, 0
	s_add_u32 s54, s70, 0x5200
	s_addc_u32 s55, s71, 0
	s_mul_i32 s3, s73, s96
	s_add_u32 s56, s70, 0x5300
	s_mul_i32 s3, s3, s72
	s_addc_u32 s57, s71, 0
	s_mov_b32 s12, 1
	v_mov_b32_e32 v16, 0
	s_branch .LBB0_1247

.LBB0_1346:
	s_cmp_eq_u32 s75, 14
	s_cbranch_scc1 .LBB0_1400
	s_waitcnt vmcnt(0)
	s_waitcnt vmcnt(0) lgkmcnt(0)
	s_barrier
	s_and_saveexec_b64 s[0:1], s[92:93]
	s_cbranch_execz .LBB0_1399
	buffer_wbl2 sc1
	s_add_i32 s3, 0, 0x27fc0
	v_mov_b32_e32 v0, s3
	s_waitcnt vmcnt(0) expcnt(0) lgkmcnt(0)
	ds_read_b32 v2, v0
	s_add_i32 s3, 0, 0x27fc4
	v_mov_b32_e32 v0, s3
	ds_read_b32 v0, v0
	s_waitcnt lgkmcnt(1)
	v_cmp_ne_u32_e32 vcc, 0, v2
	s_cbranch_vccnz .LBB0_1363
	s_add_u32 s4, s70, 0x4200
	s_addc_u32 s5, s71, 0
	s_add_u32 s6, s70, 0x4400
	s_addc_u32 s7, s71, 0
	s_add_u32 s10, s70, 0x4500
	s_addc_u32 s11, s71, 0
	s_add_u32 s22, s70, 0x4600
	s_addc_u32 s23, s71, 0
	s_add_u32 s26, s70, 0x4700
	s_addc_u32 s27, s71, 0
	s_add_u32 s28, s70, 0x4800
	s_addc_u32 s29, s71, 0
	s_add_u32 s30, s70, 0x4900
	s_addc_u32 s31, s71, 0
	s_add_u32 s36, s70, 0x4a00
	s_addc_u32 s37, s71, 0
	s_add_u32 s38, s70, 0x4b00
	s_addc_u32 s39, s71, 0
	s_add_u32 s40, s70, 0x4c00
	s_addc_u32 s41, s71, 0
	s_add_u32 s42, s70, 0x4d00
	s_addc_u32 s43, s71, 0
	s_add_u32 s48, s70, 0x4e00
	s_addc_u32 s49, s71, 0
	s_add_u32 s50, s70, 0x4f00
	s_addc_u32 s51, s71, 0
	s_add_u32 s52, s70, 0x5000
	s_addc_u32 s53, s71, 0
	s_add_u32 s54, s70, 0x5100
	s_addc_u32 s55, s71, 0
	s_add_u32 s56, s70, 0x5200
	s_addc_u32 s57, s71, 0
	s_mul_i32 s3, s73, s96
	s_add_u32 s58, s70, 0x5300
	s_mul_i32 s3, s3, s72
	s_addc_u32 s59, s71, 0
	s_mov_b32 s12, 1
	v_mov_b32_e32 v16, 0
	s_branch .LBB0_1351

.LBB0_1420:
	s_cmp_eq_u32 s75, 15
	s_cbranch_scc1 .LBB0_1474
	s_waitcnt vmcnt(0)
	s_waitcnt vmcnt(0) lgkmcnt(0)
	s_barrier
	s_and_saveexec_b64 s[0:1], s[92:93]
	s_cbranch_execz .LBB0_1473
	buffer_wbl2 sc1
	s_add_i32 s3, 0, 0x27fc0
	v_mov_b32_e32 v0, s3
	s_waitcnt vmcnt(0) expcnt(0) lgkmcnt(0)
	ds_read_b32 v2, v0
	s_add_i32 s3, 0, 0x27fc4
	v_mov_b32_e32 v0, s3
	ds_read_b32 v0, v0
	s_waitcnt lgkmcnt(1)
	v_cmp_ne_u32_e32 vcc, 0, v2
	s_cbranch_vccnz .LBB0_1437
	s_add_u32 s4, s70, 0x4200
	s_addc_u32 s5, s71, 0
	s_add_u32 s6, s70, 0x4400
	s_addc_u32 s7, s71, 0
	s_add_u32 s10, s70, 0x4500
	s_addc_u32 s11, s71, 0
	s_add_u32 s22, s70, 0x4600
	s_addc_u32 s23, s71, 0
	s_add_u32 s26, s70, 0x4700
	s_addc_u32 s27, s71, 0
	s_add_u32 s28, s70, 0x4800
	s_addc_u32 s29, s71, 0
	s_add_u32 s30, s70, 0x4900
	s_addc_u32 s31, s71, 0
	s_add_u32 s36, s70, 0x4a00
	s_addc_u32 s37, s71, 0
	s_add_u32 s38, s70, 0x4b00
	s_addc_u32 s39, s71, 0
	s_add_u32 s40, s70, 0x4c00
	s_addc_u32 s41, s71, 0
	s_add_u32 s42, s70, 0x4d00
	s_addc_u32 s43, s71, 0
	s_add_u32 s48, s70, 0x4e00
	s_addc_u32 s49, s71, 0
	s_add_u32 s50, s70, 0x4f00
	s_addc_u32 s51, s71, 0
	s_add_u32 s52, s70, 0x5000
	s_addc_u32 s53, s71, 0
	s_add_u32 s54, s70, 0x5100
	s_addc_u32 s55, s71, 0
	s_add_u32 s56, s70, 0x5200
	s_addc_u32 s57, s71, 0
	s_mul_i32 s3, s73, s96
	s_add_u32 s58, s70, 0x5300
	s_mul_i32 s3, s3, s72
	s_addc_u32 s59, s71, 0
	s_mov_b32 s12, 1
	v_mov_b32_e32 v16, 0
	s_branch .LBB0_1425

.LBB0_1482:
	s_cmp_eq_u32 s75, 16
	s_cbranch_scc1 .LBB0_1536
	s_waitcnt vmcnt(0)
	s_waitcnt vmcnt(0) lgkmcnt(0)
	s_barrier
	s_and_saveexec_b64 s[0:1], s[92:93]
	s_cbranch_execz .LBB0_1535
	buffer_wbl2 sc1
	s_add_i32 s3, 0, 0x27fc0
	v_mov_b32_e32 v0, s3
	s_waitcnt vmcnt(0) expcnt(0) lgkmcnt(0)
	ds_read_b32 v2, v0
	s_add_i32 s3, 0, 0x27fc4
	v_mov_b32_e32 v0, s3
	ds_read_b32 v0, v0
	s_waitcnt lgkmcnt(1)
	v_cmp_ne_u32_e32 vcc, 0, v2
	s_cbranch_vccnz .LBB0_1499
	s_add_u32 s4, s70, 0x4200
	s_addc_u32 s5, s71, 0
	s_add_u32 s6, s70, 0x4400
	s_addc_u32 s7, s71, 0
	s_add_u32 s8, s70, 0x4500
	s_addc_u32 s9, s71, 0
	s_add_u32 s10, s70, 0x4600
	s_addc_u32 s11, s71, 0
	s_add_u32 s22, s70, 0x4700
	s_addc_u32 s23, s71, 0
	s_add_u32 s26, s70, 0x4800
	s_addc_u32 s27, s71, 0
	s_add_u32 s28, s70, 0x4900
	s_addc_u32 s29, s71, 0
	s_add_u32 s30, s70, 0x4a00
	s_addc_u32 s31, s71, 0
	s_add_u32 s36, s70, 0x4b00
	s_addc_u32 s37, s71, 0
	s_add_u32 s38, s70, 0x4c00
	s_addc_u32 s39, s71, 0
	s_add_u32 s40, s70, 0x4d00
	s_addc_u32 s41, s71, 0
	s_add_u32 s42, s70, 0x4e00
	s_addc_u32 s43, s71, 0
	s_add_u32 s44, s70, 0x4f00
	s_addc_u32 s45, s71, 0
	s_add_u32 s46, s70, 0x5000
	s_addc_u32 s47, s71, 0
	s_add_u32 s48, s70, 0x5100
	s_addc_u32 s49, s71, 0
	s_add_u32 s50, s70, 0x5200
	s_addc_u32 s51, s71, 0
	s_mul_i32 s3, s73, s96
	s_add_u32 s52, s70, 0x5300
	s_mul_i32 s3, s3, s72
	s_addc_u32 s53, s71, 0
	s_mov_b32 s12, 1
	v_mov_b32_e32 v16, 0
	s_branch .LBB0_1487

.LBB0_1580:
	s_waitcnt vmcnt(0)
	s_waitcnt vmcnt(0) lgkmcnt(0)
	s_barrier
	s_and_saveexec_b64 s[0:1], s[92:93]
	s_cbranch_execz .LBB0_1632
	buffer_wbl2 sc1
	s_add_i32 s3, 0, 0x27fc0
	v_mov_b32_e32 v0, s3
	s_waitcnt vmcnt(0) expcnt(0) lgkmcnt(0)
	ds_read_b32 v2, v0
	s_add_i32 s3, 0, 0x27fc4
	v_mov_b32_e32 v0, s3
	ds_read_b32 v0, v0
	s_waitcnt lgkmcnt(1)
	v_cmp_ne_u32_e32 vcc, 0, v2
	s_cbranch_vccnz .LBB0_1596
	s_add_u32 s4, s70, 0x4200
	s_addc_u32 s5, s71, 0
	s_add_u32 s6, s70, 0x4400
	s_addc_u32 s7, s71, 0
	s_add_u32 s8, s70, 0x4500
	s_addc_u32 s9, s71, 0
	s_add_u32 s10, s70, 0x4600
	s_addc_u32 s11, s71, 0
	s_add_u32 s22, s70, 0x4700
	s_addc_u32 s23, s71, 0
	s_add_u32 s26, s70, 0x4800
	s_addc_u32 s27, s71, 0
	s_add_u32 s28, s70, 0x4900
	s_addc_u32 s29, s71, 0
	s_add_u32 s30, s70, 0x4a00
	s_addc_u32 s31, s71, 0
	s_add_u32 s36, s70, 0x4b00
	s_addc_u32 s37, s71, 0
	s_add_u32 s38, s70, 0x4c00
	s_addc_u32 s39, s71, 0
	s_add_u32 s40, s70, 0x4d00
	s_addc_u32 s41, s71, 0
	s_add_u32 s42, s70, 0x4e00
	s_addc_u32 s43, s71, 0
	s_add_u32 s44, s70, 0x4f00
	s_addc_u32 s45, s71, 0
	s_add_u32 s46, s70, 0x5000
	s_addc_u32 s47, s71, 0
	s_add_u32 s48, s70, 0x5100
	s_addc_u32 s49, s71, 0
	s_add_u32 s50, s70, 0x5200
	s_addc_u32 s51, s71, 0
	s_mul_i32 s3, s73, s96
	s_add_u32 s52, s70, 0x5300
	s_mul_i32 s3, s3, s72
	s_addc_u32 s53, s71, 0
	s_mov_b32 s12, 1
	v_mov_b32_e32 v16, 0
	s_branch .LBB0_1584

.LBB0_1654:
	s_cmp_eq_u32 s75, 18
	s_cbranch_scc1 .LBB0_1708
	s_waitcnt vmcnt(0)
	s_waitcnt vmcnt(0)
	s_barrier
	s_and_saveexec_b64 s[0:1], s[92:93]
	s_cbranch_execz .LBB0_1707
	buffer_wbl2 sc1
	s_add_i32 s3, 0, 0x27fc0
	v_mov_b32_e32 v0, s3
	s_waitcnt vmcnt(0) expcnt(0) lgkmcnt(0)
	ds_read_b32 v2, v0
	s_add_i32 s3, 0, 0x27fc4
	v_mov_b32_e32 v0, s3
	ds_read_b32 v0, v0
	s_waitcnt lgkmcnt(1)
	v_cmp_ne_u32_e32 vcc, 0, v2
	s_cbranch_vccnz .LBB0_1671
	s_add_u32 s4, s70, 0x4200
	s_addc_u32 s5, s71, 0
	s_add_u32 s6, s70, 0x4400
	s_addc_u32 s7, s71, 0
	s_add_u32 s8, s70, 0x4500
	s_addc_u32 s9, s71, 0
	s_add_u32 s10, s70, 0x4600
	s_addc_u32 s11, s71, 0
	s_add_u32 s22, s70, 0x4700
	s_addc_u32 s23, s71, 0
	s_add_u32 s26, s70, 0x4800
	s_addc_u32 s27, s71, 0
	s_add_u32 s28, s70, 0x4900
	s_addc_u32 s29, s71, 0
	s_add_u32 s30, s70, 0x4a00
	s_addc_u32 s31, s71, 0
	s_add_u32 s36, s70, 0x4b00
	s_addc_u32 s37, s71, 0
	s_add_u32 s38, s70, 0x4c00
	s_addc_u32 s39, s71, 0
	s_add_u32 s40, s70, 0x4d00
	s_addc_u32 s41, s71, 0
	s_add_u32 s42, s70, 0x4e00
	s_addc_u32 s43, s71, 0
	s_add_u32 s44, s70, 0x4f00
	s_addc_u32 s45, s71, 0
	s_add_u32 s46, s70, 0x5000
	s_addc_u32 s47, s71, 0
	s_add_u32 s48, s70, 0x5100
	s_addc_u32 s49, s71, 0
	s_add_u32 s50, s70, 0x5200
	s_addc_u32 s51, s71, 0
	s_mul_i32 s3, s73, s96
	s_add_u32 s52, s70, 0x5300
	s_mul_i32 s3, s3, s72
	s_addc_u32 s53, s71, 0
	s_mov_b32 s12, 1
	v_mov_b32_e32 v16, 0
	s_branch .LBB0_1659

.LBB0_1926:
	s_or_b64 exec, exec, s[0:1]
	s_cmp_eq_u32 s75, 21
	s_cbranch_scc1 .LBB0_1980
	s_waitcnt vmcnt(0)
	s_waitcnt vmcnt(0) lgkmcnt(0)
	s_barrier
	s_and_saveexec_b64 s[0:1], s[92:93]
	s_cbranch_execz .LBB0_1979
	buffer_wbl2 sc1
	s_add_i32 s3, 0, 0x27fc0
	v_mov_b32_e32 v0, s3
	s_waitcnt vmcnt(0) expcnt(0) lgkmcnt(0)
	ds_read_b32 v2, v0
	s_add_i32 s3, 0, 0x27fc4
	v_mov_b32_e32 v0, s3
	ds_read_b32 v0, v0
	s_waitcnt lgkmcnt(1)
	v_cmp_ne_u32_e32 vcc, 0, v2
	s_cbranch_vccnz .LBB0_1943
	s_add_u32 s4, s70, 0x4200
	s_addc_u32 s5, s71, 0
	s_add_u32 s6, s70, 0x4400
	s_addc_u32 s7, s71, 0
	s_add_u32 s8, s70, 0x4500
	s_addc_u32 s9, s71, 0
	s_add_u32 s10, s70, 0x4600
	s_addc_u32 s11, s71, 0
	s_add_u32 s22, s70, 0x4700
	s_addc_u32 s23, s71, 0
	s_add_u32 s24, s70, 0x4800
	s_addc_u32 s25, s71, 0
	s_add_u32 s26, s70, 0x4900
	s_addc_u32 s27, s71, 0
	s_add_u32 s28, s70, 0x4a00
	s_addc_u32 s29, s71, 0
	s_add_u32 s30, s70, 0x4b00
	s_addc_u32 s31, s71, 0
	s_add_u32 s36, s70, 0x4c00
	s_addc_u32 s37, s71, 0
	s_add_u32 s38, s70, 0x4d00
	s_addc_u32 s39, s71, 0
	s_add_u32 s40, s70, 0x4e00
	s_addc_u32 s41, s71, 0
	s_add_u32 s42, s70, 0x4f00
	s_addc_u32 s43, s71, 0
	s_add_u32 s44, s70, 0x5000
	s_addc_u32 s45, s71, 0
	s_add_u32 s46, s70, 0x5100
	s_addc_u32 s47, s71, 0
	s_add_u32 s48, s70, 0x5200
	s_addc_u32 s49, s71, 0
	s_mul_i32 s3, s73, s96
	s_add_u32 s50, s70, 0x5300
	s_mul_i32 s3, s3, s72
	s_addc_u32 s51, s71, 0
	s_mov_b32 s12, 1
	v_mov_b32_e32 v16, 0
	s_branch .LBB0_1931

.LBB0_2024:
	s_waitcnt vmcnt(0)
	s_waitcnt vmcnt(0) lgkmcnt(0)
	s_barrier
	s_and_saveexec_b64 s[0:1], s[92:93]
	s_cbranch_execz .LBB0_2076
	buffer_wbl2 sc1
	s_add_i32 s3, 0, 0x27fc0
	v_mov_b32_e32 v0, s3
	s_waitcnt vmcnt(0) expcnt(0) lgkmcnt(0)
	ds_read_b32 v2, v0
	s_add_i32 s3, 0, 0x27fc4
	v_mov_b32_e32 v0, s3
	ds_read_b32 v0, v0
	s_waitcnt lgkmcnt(1)
	v_cmp_ne_u32_e32 vcc, 0, v2
	s_cbranch_vccnz .LBB0_2040
	s_add_u32 s4, s70, 0x4200
	s_addc_u32 s5, s71, 0
	s_add_u32 s6, s70, 0x4400
	s_addc_u32 s7, s71, 0
	s_add_u32 s8, s70, 0x4500
	s_addc_u32 s9, s71, 0
	s_add_u32 s10, s70, 0x4600
	s_addc_u32 s11, s71, 0
	s_add_u32 s20, s70, 0x4700
	s_addc_u32 s21, s71, 0
	s_add_u32 s22, s70, 0x4800
	s_addc_u32 s23, s71, 0
	s_add_u32 s24, s70, 0x4900
	s_addc_u32 s25, s71, 0
	s_add_u32 s26, s70, 0x4a00
	s_addc_u32 s27, s71, 0
	s_add_u32 s28, s70, 0x4b00
	s_addc_u32 s29, s71, 0
	s_add_u32 s30, s70, 0x4c00
	s_addc_u32 s31, s71, 0
	s_add_u32 s36, s70, 0x4d00
	s_addc_u32 s37, s71, 0
	s_add_u32 s38, s70, 0x4e00
	s_addc_u32 s39, s71, 0
	s_add_u32 s40, s70, 0x4f00
	s_addc_u32 s41, s71, 0
	s_add_u32 s42, s70, 0x5000
	s_addc_u32 s43, s71, 0
	s_add_u32 s44, s70, 0x5100
	s_addc_u32 s45, s71, 0
	s_add_u32 s46, s70, 0x5200
	s_addc_u32 s47, s71, 0
	s_mul_i32 s3, s73, s96
	s_add_u32 s48, s70, 0x5300
	s_mul_i32 s3, s3, s72
	s_addc_u32 s49, s71, 0
	s_mov_b32 s12, 1
	v_mov_b32_e32 v16, 0
	s_branch .LBB0_2028

.LBB0_2098:
	s_cmp_eq_u32 s75, 23
	s_cbranch_scc1 .LBB0_2152
	s_waitcnt vmcnt(0)
	s_waitcnt vmcnt(0)
	s_barrier
	s_and_saveexec_b64 s[0:1], s[92:93]
	s_cbranch_execz .LBB0_2151
	buffer_wbl2 sc1
	s_add_i32 s3, 0, 0x27fc0
	v_mov_b32_e32 v0, s3
	s_waitcnt vmcnt(0) expcnt(0) lgkmcnt(0)
	ds_read_b32 v2, v0
	s_add_i32 s3, 0, 0x27fc4
	v_mov_b32_e32 v0, s3
	ds_read_b32 v0, v0
	s_waitcnt lgkmcnt(1)
	v_cmp_ne_u32_e32 vcc, 0, v2
	s_cbranch_vccnz .LBB0_2115
	s_add_u32 s4, s70, 0x4200
	s_addc_u32 s5, s71, 0
	s_add_u32 s6, s70, 0x4400
	s_addc_u32 s7, s71, 0
	s_add_u32 s8, s70, 0x4500
	s_addc_u32 s9, s71, 0
	s_add_u32 s10, s70, 0x4600
	s_addc_u32 s11, s71, 0
	s_add_u32 s18, s70, 0x4700
	s_addc_u32 s19, s71, 0
	s_add_u32 s20, s70, 0x4800
	s_addc_u32 s21, s71, 0
	s_add_u32 s22, s70, 0x4900
	s_addc_u32 s23, s71, 0
	s_add_u32 s24, s70, 0x4a00
	s_addc_u32 s25, s71, 0
	s_add_u32 s26, s70, 0x4b00
	s_addc_u32 s27, s71, 0
	s_add_u32 s28, s70, 0x4c00
	s_addc_u32 s29, s71, 0
	s_add_u32 s30, s70, 0x4d00
	s_addc_u32 s31, s71, 0
	s_add_u32 s36, s70, 0x4e00
	s_addc_u32 s37, s71, 0
	s_add_u32 s38, s70, 0x4f00
	s_addc_u32 s39, s71, 0
	s_add_u32 s40, s70, 0x5000
	s_addc_u32 s41, s71, 0
	s_add_u32 s42, s70, 0x5100
	s_addc_u32 s43, s71, 0
	s_add_u32 s44, s70, 0x5200
	s_addc_u32 s45, s71, 0
	s_mul_i32 s3, s73, s96
	s_add_u32 s46, s70, 0x5300
	s_mul_i32 s3, s3, s72
	s_addc_u32 s47, s71, 0
	s_mov_b32 s12, 1
	v_mov_b32_e32 v16, 0
	s_branch .LBB0_2103

.LBB0_2181:
	s_cmp_eq_u32 s75, 24
	s_cbranch_scc1 .LBB0_2235
	s_waitcnt vmcnt(0)
	s_waitcnt vmcnt(0) lgkmcnt(0)
	s_barrier
	s_and_saveexec_b64 s[0:1], s[92:93]
	s_cbranch_execz .LBB0_2234
	buffer_wbl2 sc1
	s_add_i32 s2, 0, 0x27fc0
	v_mov_b32_e32 v0, s2
	s_waitcnt vmcnt(0) expcnt(0) lgkmcnt(0)
	ds_read_b32 v2, v0
	s_add_i32 s2, 0, 0x27fc4
	v_mov_b32_e32 v0, s2
	ds_read_b32 v0, v0
	s_waitcnt lgkmcnt(1)
	v_cmp_ne_u32_e32 vcc, 0, v2
	s_cbranch_vccnz .LBB0_2198
	s_add_u32 s2, s70, 0x4200
	s_addc_u32 s3, s71, 0
	s_add_u32 s4, s70, 0x4400
	s_addc_u32 s5, s71, 0
	s_add_u32 s6, s70, 0x4500
	s_addc_u32 s7, s71, 0
	s_add_u32 s8, s70, 0x4600
	s_addc_u32 s9, s71, 0
	s_add_u32 s10, s70, 0x4700
	s_addc_u32 s11, s71, 0
	s_add_u32 s12, s70, 0x4800
	s_addc_u32 s13, s71, 0
	s_add_u32 s14, s70, 0x4900
	s_addc_u32 s15, s71, 0
	s_add_u32 s16, s70, 0x4a00
	s_addc_u32 s17, s71, 0
	s_add_u32 s18, s70, 0x4b00
	s_addc_u32 s19, s71, 0
	s_add_u32 s20, s70, 0x4c00
	s_addc_u32 s21, s71, 0
	s_add_u32 s22, s70, 0x4d00
	s_addc_u32 s23, s71, 0
	s_add_u32 s24, s70, 0x4e00
	s_addc_u32 s25, s71, 0
	s_add_u32 s26, s70, 0x4f00
	s_addc_u32 s27, s71, 0
	s_add_u32 s28, s70, 0x5000
	s_addc_u32 s29, s71, 0
	s_add_u32 s30, s70, 0x5100
	s_addc_u32 s31, s71, 0
	s_add_u32 s36, s70, 0x5200
	s_addc_u32 s37, s71, 0
	s_mul_i32 s34, s73, s96
	s_add_u32 s38, s70, 0x5300
	s_mul_i32 s34, s34, s72
	s_addc_u32 s39, s71, 0
	s_mov_b32 s35, 1
	v_mov_b32_e32 v16, 0
	s_branch .LBB0_2186
